# ssd pass1/pass3 head loops: fast path (8 plain loads) for the next head's conv-tap rows when the tap masks are all-ones
# baseline (speedup 1.0000x reference)
.LBB0_960:
	v_lshl_add_u64 v[2:3], v[76:77], 0, s[38:39]
	v_lshl_add_u64 v[40:41], v[82:83], 0, s[38:39]
	v_mov_b32_e32 v1, s33
	ds_read_b32 v1, v1 offset:4604
	ds_read_b128 v[36:39], v222 offset:1152
	s_nop 0
	ds_read_b128 v[40:43], v222 offset:1024
	s_nop 0
	ds_read_b128 v[44:47], v222 offset:128
	ds_read_b128 v[48:51], v222
	s_waitcnt vmcnt(4)
	v_lshlrev_b32_e32 v52, 16, v8
	s_mov_b64 s[40:41], 0x1800
	v_and_b32_e32 v53, 0xffff0000, v8
	v_lshl_add_u64 v[56:57], v[2:3], 0, s[40:41]
	v_lshlrev_b32_e32 v54, 16, v9
	v_and_b32_e32 v55, 0xffff0000, v9
	v_lshlrev_b32_e32 v58, 16, v10
	v_and_b32_e32 v59, 0xffff0000, v10
	s_mov_b64 s[40:41], 0x3000
	v_lshl_add_u64 v[64:65], v[2:3], 0, s[40:41]
	s_mov_b64 s[40:41], 0x4800
	v_lshlrev_b32_e32 v60, 16, v11
	v_lshl_add_u64 v[72:73], v[2:3], 0, s[40:41]
	v_and_b32_e32 v61, 0xffff0000, v11
	s_movk_i32 s40, 0x3000
	v_lshlrev_b32_e32 v62, 16, v5
	v_and_b32_e32 v63, 0xffff0000, v5
	v_lshlrev_b32_e32 v66, 16, v6
	v_and_b32_e32 v67, 0xffff0000, v6
	v_lshlrev_b32_e32 v68, 16, v7
	v_and_b32_e32 v69, 0xffff0000, v7
	v_lshlrev_b32_e32 v70, 16, v13
	v_and_b32_e32 v71, 0xffff0000, v13
	v_lshlrev_b32_e32 v74, 16, v14
	v_and_b32_e32 v75, 0xffff0000, v14
	v_lshlrev_b32_e32 v84, 16, v15
	v_and_b32_e32 v85, 0xffff0000, v15
	v_lshlrev_b32_e32 v101, 16, v17
	v_and_b32_e32 v102, 0xffff0000, v17
	v_lshlrev_b32_e32 v103, 16, v18
	v_and_b32_e32 v104, 0xffff0000, v18
	v_lshlrev_b32_e32 v105, 16, v19
	v_and_b32_e32 v106, 0xffff0000, v19
	s_cmpk_eq_i32 s38, 0x700
	s_waitcnt lgkmcnt(0)
	v_fma_f32 v96, v44, v58, v36
	s_nop 0
	v_fma_f32 v100, v48, v52, v40
	v_add_co_u32_e32 v52, vcc, s69, v2
	v_fma_f32 v99, v49, v53, v41
	s_nop 0
	v_addc_co_u32_e32 v53, vcc, 0, v3, vcc
	v_fma_f32 v95, v45, v59, v37
	v_fma_f32 v98, v50, v54, v42
	v_fma_f32 v97, v51, v55, v43
	ds_read_b128 v[52:55], v222 offset:256
	s_nop 0
	ds_read_b128 v[56:59], v222 offset:384
	v_fma_f32 v94, v46, v60, v38
	v_lshlrev_b32_e32 v60, 16, v4
	v_fma_f32 v93, v47, v61, v39
	v_and_b32_e32 v61, 0xffff0000, v4
	s_waitcnt lgkmcnt(0)
	v_fmac_f32_e32 v100, v52, v60
	v_add_co_u32_e32 v60, vcc, s40, v2
	v_fmac_f32_e32 v99, v53, v61
	s_nop 0
	v_addc_co_u32_e32 v61, vcc, 0, v3, vcc
	s_nop 0
	v_fmac_f32_e32 v96, v56, v66
	v_fmac_f32_e32 v95, v57, v67
	v_fmac_f32_e32 v98, v54, v62
	v_fmac_f32_e32 v97, v55, v63
	ds_read_b128 v[60:63], v222 offset:512
	s_nop 0
	ds_read_b128 v[64:67], v222 offset:640
	s_movk_i32 s40, 0x4000
	v_add_co_u32_e32 v2, vcc, s40, v2
	v_fmac_f32_e32 v94, v58, v68
	v_fmac_f32_e32 v93, v59, v69
	v_lshlrev_b32_e32 v68, 16, v12
	v_and_b32_e32 v69, 0xffff0000, v12
	v_addc_co_u32_e32 v3, vcc, 0, v3, vcc
	s_waitcnt lgkmcnt(0)
	v_fmac_f32_e32 v100, v60, v68
	s_nop 0
	v_fmac_f32_e32 v96, v64, v74
	v_fmac_f32_e32 v99, v61, v69
	v_fmac_f32_e32 v95, v65, v75
	v_fmac_f32_e32 v98, v62, v70
	v_fmac_f32_e32 v97, v63, v71
	ds_read_b128 v[68:71], v222 offset:768
	s_nop 0
	ds_read_b128 v[72:75], v222 offset:896
	v_add_u32_e32 v222, 0x500, v222
	v_fmac_f32_e32 v94, v66, v84
	v_lshlrev_b32_e32 v84, 16, v16
	v_fmac_f32_e32 v93, v67, v85
	v_and_b32_e32 v85, 0xffff0000, v16
	s_waitcnt lgkmcnt(0)
	v_fmac_f32_e32 v100, v68, v84
	v_add_u32_e32 v84, s33, v87
	v_fmac_f32_e32 v99, v69, v85
	ds_read2st64_b32 v[2:3], v84 offset1:1
	ds_read2st64_b32 v[84:85], v84 offset0:16 offset1:17
	v_fmac_f32_e32 v98, v70, v101
	v_fmac_f32_e32 v97, v71, v102
	s_nop 0
	v_fmac_f32_e32 v96, v72, v103
	v_fmac_f32_e32 v95, v73, v104
	s_waitcnt lgkmcnt(0)
	v_sub_f32_e32 v84, v1, v84
	v_mul_f32_e32 v84, 0x3fb8aa3b, v84
	v_exp_f32_e32 v84, v84
	v_fmac_f32_e32 v94, v74, v105
	v_fmac_f32_e32 v93, v75, v106
	v_sub_f32_e32 v1, v1, v85
	v_mul_f32_e32 v2, v2, v84
	v_mul_f32_e32 v84, 0xbfb8aa3b, v100
	v_exp_f32_e32 v84, v84
	v_mul_f32_e32 v1, 0x3fb8aa3b, v1
	v_exp_f32_e32 v1, v1
	v_add_f32_e32 v84, 1.0, v84
	v_rcp_f32_e32 v84, v84
	v_mul_f32_e32 v1, v3, v1
	v_mul_f32_e32 v84, v100, v84
	v_mul_f32_e32 v84, v2, v84
	v_cvt_pk_bf16_f32 v84, v84, s0
	ds_write_b16 v88, v84 offset:34816
	v_mul_f32_e32 v84, 0xbfb8aa3b, v99
	v_exp_f32_e32 v84, v84
	s_nop 0
	v_add_f32_e32 v84, 1.0, v84
	v_rcp_f32_e32 v84, v84
	s_nop 0
	v_mul_f32_e32 v84, v99, v84
	v_mul_f32_e32 v84, v2, v84
	v_cvt_pk_bf16_f32 v84, v84, s0
	ds_write_b16 v88, v84 offset:35088
	v_mul_f32_e32 v84, 0xbfb8aa3b, v98
	v_exp_f32_e32 v84, v84
	s_nop 0
	v_add_f32_e32 v84, 1.0, v84
	v_rcp_f32_e32 v84, v84
	s_nop 0
	v_mul_f32_e32 v84, v98, v84
	v_mul_f32_e32 v84, v2, v84
	v_cvt_pk_bf16_f32 v84, v84, s0
	ds_write_b16 v88, v84 offset:35360
	v_mul_f32_e32 v84, 0xbfb8aa3b, v97
	v_exp_f32_e32 v84, v84
	v_and_b32_e32 v98, 0xffff0000, v23
	v_fmac_f32_e32 v39, v47, v98
	v_lshlrev_b32_e32 v47, 16, v26
	v_add_f32_e32 v84, 1.0, v84
	v_rcp_f32_e32 v84, v84
	s_nop 0
	v_mul_f32_e32 v84, v97, v84
	v_mul_f32_e32 v84, v2, v84
	v_cvt_pk_bf16_f32 v84, v84, s0
	ds_write_b16 v88, v84 offset:35632
	v_mul_f32_e32 v84, 0xbfb8aa3b, v96
	v_exp_f32_e32 v84, v84
	v_lshlrev_b32_e32 v97, 16, v23
	v_fma_f32 v38, v46, v97, v38
	v_and_b32_e32 v46, 0xffff0000, v25
	v_add_f32_e32 v84, 1.0, v84
	v_rcp_f32_e32 v84, v84
	s_nop 0
	v_mul_f32_e32 v84, v96, v84
	v_mul_f32_e32 v84, v2, v84
	v_cvt_pk_bf16_f32 v84, v84, s0
	ds_write_b16 v88, v84 offset:35904
	v_mul_f32_e32 v84, 0xbfb8aa3b, v95
	v_exp_f32_e32 v84, v84
	v_and_b32_e32 v96, 0xffff0000, v22
	v_fma_f32 v37, v45, v96, v37
	v_lshlrev_b32_e32 v45, 16, v25
	v_add_f32_e32 v84, 1.0, v84
	v_rcp_f32_e32 v84, v84
	s_nop 0
	v_mul_f32_e32 v84, v95, v84
	v_mul_f32_e32 v84, v2, v84
	v_cvt_pk_bf16_f32 v84, v84, s0
	ds_write_b16 v88, v84 offset:36176
	v_mul_f32_e32 v84, 0xbfb8aa3b, v94
	v_exp_f32_e32 v84, v84
	v_lshlrev_b32_e32 v95, 16, v22
	v_fma_f32 v36, v44, v95, v36
	v_and_b32_e32 v44, 0xffff0000, v24
	v_add_f32_e32 v84, 1.0, v84
	v_rcp_f32_e32 v84, v84
	v_fmac_f32_e32 v36, v56, v47
	v_lshlrev_b32_e32 v47, 16, v30
	v_fmac_f32_e32 v36, v64, v47
	v_mul_f32_e32 v84, v94, v84
	v_mul_f32_e32 v84, v2, v84
	v_cvt_pk_bf16_f32 v84, v84, s0
	ds_write_b16 v88, v84 offset:36448
	v_mul_f32_e32 v84, 0xbfb8aa3b, v93
	v_exp_f32_e32 v84, v84
	v_and_b32_e32 v94, 0xffff0000, v21
	v_fmac_f32_e32 v43, v51, v94
	v_fmac_f32_e32 v43, v55, v46
	v_add_f32_e32 v84, 1.0, v84
	v_rcp_f32_e32 v84, v84
	v_and_b32_e32 v46, 0xffff0000, v29
	v_fmac_f32_e32 v43, v63, v46
	v_and_b32_e32 v46, 0xffff0000, v33
	v_mul_f32_e32 v84, v93, v84
	v_mul_f32_e32 v2, v2, v84
	v_cvt_pk_bf16_f32 v2, v2, s0
	ds_write_b16 v88, v2 offset:36720
	v_lshlrev_b32_e32 v2, 16, v20
	v_and_b32_e32 v84, 0xffff0000, v20
	v_lshlrev_b32_e32 v93, 16, v21
	v_fma_f32 v2, v48, v2, v40
	v_fma_f32 v40, v49, v84, v41
	v_fma_f32 v41, v50, v93, v42
	v_lshlrev_b32_e32 v42, 16, v24
	v_fmac_f32_e32 v2, v52, v42
	v_lshlrev_b32_e32 v42, 16, v28
	v_fmac_f32_e32 v2, v60, v42
	v_lshlrev_b32_e32 v42, 16, v32
	v_fmac_f32_e32 v2, v68, v42
	v_mul_f32_e32 v3, 0xbfb8aa3b, v2
	v_exp_f32_e32 v3, v3
	v_fmac_f32_e32 v40, v53, v44
	v_and_b32_e32 v44, 0xffff0000, v28
	v_fmac_f32_e32 v40, v61, v44
	v_add_f32_e32 v3, 1.0, v3
	v_rcp_f32_e32 v3, v3
	v_and_b32_e32 v44, 0xffff0000, v32
	v_fmac_f32_e32 v40, v69, v44
	v_fmac_f32_e32 v41, v54, v45
	v_mul_f32_e32 v2, v2, v3
	v_mul_f32_e32 v2, v2, v1
	v_cvt_pk_bf16_f32 v2, v2, s0
	ds_write_b16 v88, v2 offset:34944
	v_mul_f32_e32 v2, 0xbfb8aa3b, v40
	v_exp_f32_e32 v2, v2
	v_lshlrev_b32_e32 v45, 16, v29
	v_fmac_f32_e32 v41, v62, v45
	v_lshlrev_b32_e32 v45, 16, v33
	v_add_f32_e32 v2, 1.0, v2
	v_rcp_f32_e32 v2, v2
	v_fmac_f32_e32 v41, v70, v45
	v_fmac_f32_e32 v43, v71, v46
	v_lshlrev_b32_e32 v47, 16, v34
	v_mul_f32_e32 v2, v40, v2
	v_mul_f32_e32 v2, v2, v1
	v_cvt_pk_bf16_f32 v2, v2, s0
	ds_write_b16 v88, v2 offset:35216
	v_mul_f32_e32 v2, 0xbfb8aa3b, v41
	v_exp_f32_e32 v2, v2
	v_fmac_f32_e32 v36, v72, v47
	v_and_b32_e32 v48, 0xffff0000, v26
	v_fmac_f32_e32 v37, v57, v48
	v_add_f32_e32 v2, 1.0, v2
	v_rcp_f32_e32 v2, v2
	v_and_b32_e32 v48, 0xffff0000, v30
	v_fmac_f32_e32 v37, v65, v48
	v_and_b32_e32 v48, 0xffff0000, v34
	v_mul_f32_e32 v2, v41, v2
	v_mul_f32_e32 v2, v2, v1
	v_cvt_pk_bf16_f32 v2, v2, s0
	ds_write_b16 v88, v2 offset:35488
	v_mul_f32_e32 v2, 0xbfb8aa3b, v43
	v_exp_f32_e32 v2, v2
	v_fmac_f32_e32 v37, v73, v48
	v_lshlrev_b32_e32 v49, 16, v27
	v_fmac_f32_e32 v38, v58, v49
	v_add_f32_e32 v2, 1.0, v2
	v_rcp_f32_e32 v2, v2
	v_lshlrev_b32_e32 v49, 16, v31
	v_fmac_f32_e32 v38, v66, v49
	v_lshlrev_b32_e32 v49, 16, v35
	v_mul_f32_e32 v2, v43, v2
	v_mul_f32_e32 v2, v2, v1
	v_cvt_pk_bf16_f32 v2, v2, s0
	ds_write_b16 v88, v2 offset:35760
	v_mul_f32_e32 v2, 0xbfb8aa3b, v36
	v_exp_f32_e32 v2, v2
	v_fmac_f32_e32 v38, v74, v49
	v_and_b32_e32 v50, 0xffff0000, v27
	v_fmac_f32_e32 v39, v59, v50
	v_add_f32_e32 v2, 1.0, v2
	v_rcp_f32_e32 v2, v2
	v_and_b32_e32 v50, 0xffff0000, v31
	v_fmac_f32_e32 v39, v67, v50
	v_and_b32_e32 v50, 0xffff0000, v35
	v_mul_f32_e32 v2, v36, v2
	v_mul_f32_e32 v2, v2, v1
	v_cvt_pk_bf16_f32 v2, v2, s0
	ds_write_b16 v88, v2 offset:36032
	v_mul_f32_e32 v2, 0xbfb8aa3b, v37
	v_exp_f32_e32 v2, v2
	v_fmac_f32_e32 v39, v75, v50
	v_add_f32_e32 v2, 1.0, v2
	v_rcp_f32_e32 v2, v2
	s_nop 0
	v_mul_f32_e32 v2, v37, v2
	v_mul_f32_e32 v2, v2, v1
	v_cvt_pk_bf16_f32 v2, v2, s0
	ds_write_b16 v88, v2 offset:36304
	v_mul_f32_e32 v2, 0xbfb8aa3b, v38
	v_exp_f32_e32 v2, v2
	s_nop 0
	v_add_f32_e32 v2, 1.0, v2
	v_rcp_f32_e32 v2, v2
	s_nop 0
	v_mul_f32_e32 v2, v38, v2
	v_mul_f32_e32 v2, v2, v1
	v_cvt_pk_bf16_f32 v2, v2, s0
	ds_write_b16 v88, v2 offset:36576
	v_mul_f32_e32 v2, 0xbfb8aa3b, v39
	v_exp_f32_e32 v2, v2
	s_nop 0
	v_add_f32_e32 v2, 1.0, v2
	v_rcp_f32_e32 v2, v2
	s_nop 0
	v_mul_f32_e32 v2, v39, v2
	v_mul_f32_e32 v1, v2, v1
	v_cvt_pk_bf16_f32 v1, v1, s0
	ds_write_b16 v88, v1 offset:36848
	s_waitcnt lgkmcnt(0)
	s_barrier
	s_cbranch_scc1 .LBB0_959
	s_cmp_eq_u64 s[4:5], -1
	s_cbranch_scc0 .Lp1x_slow
	v_lshl_add_u64 v[36:37], s[2:3], 0, v[80:81]
	s_mov_b32 s40, 0x31fac80
	s_mov_b32 s41, 0
	v_lshl_add_u64 v[2:3], v[36:37], 0, s[40:41]
	global_load_dwordx4 v[8:11], v[2:3], off
	s_mov_b32 s40, 0x31fd080
	s_mov_b32 s41, 0
	v_lshl_add_u64 v[2:3], v[36:37], 0, s[40:41]
	global_load_dwordx4 v[4:7], v[2:3], off
	s_mov_b32 s40, 0x31ff480
	s_mov_b32 s41, 0
	v_lshl_add_u64 v[2:3], v[36:37], 0, s[40:41]
	global_load_dwordx4 v[12:15], v[2:3], off
	s_mov_b32 s40, 0x3201880
	s_mov_b32 s41, 0
	v_lshl_add_u64 v[2:3], v[36:37], 0, s[40:41]
	global_load_dwordx4 v[16:19], v[2:3], off
	s_mov_b32 s40, 0x328ac80
	s_mov_b32 s41, 0
	v_lshl_add_u64 v[2:3], v[36:37], 0, s[40:41]
	global_load_dwordx4 v[20:23], v[2:3], off
	s_mov_b32 s40, 0x328d080
	s_mov_b32 s41, 0
	v_lshl_add_u64 v[2:3], v[36:37], 0, s[40:41]
	global_load_dwordx4 v[24:27], v[2:3], off
	s_mov_b32 s40, 0x328f480
	s_mov_b32 s41, 0
	v_lshl_add_u64 v[2:3], v[36:37], 0, s[40:41]
	global_load_dwordx4 v[28:31], v[2:3], off
	s_mov_b32 s40, 0x3291880
	s_mov_b32 s41, 0
	v_lshl_add_u64 v[2:3], v[36:37], 0, s[40:41]
	global_load_dwordx4 v[32:35], v[2:3], off
	s_branch .LBB0_959
.Lp1x_slow:
	v_mov_b32_e32 v6, v0
	v_mov_b32_e32 v7, v0
	v_mov_b32_e32 v4, v0
	v_mov_b32_e32 v5, v0
	v_mov_b64_e32 v[10:11], v[6:7]
	v_lshl_add_u64 v[36:37], s[2:3], 0, v[80:81]
	v_mov_b64_e32 v[8:9], v[4:5]
	s_and_saveexec_b64 s[40:41], s[4:5]
	s_cbranch_execz .LBB0_963
	v_add_co_u32_e32 v2, vcc, 0x31fa000, v36
	s_nop 1
	v_addc_co_u32_e32 v3, vcc, 0, v37, vcc
	global_load_dwordx4 v[8:11], v[2:3], off offset:3200

.LBB0_1126:
	v_lshl_add_u64 v[2:3], s[6:7], 0, v[158:159]
	s_mov_b64 s[10:11], 0x1800
	v_lshl_add_u64 v[104:105], v[2:3], 0, s[10:11]
	s_movk_i32 s10, 0x1000
	v_add_co_u32_e32 v100, vcc, s10, v2
	s_mov_b64 s[10:11], 0x3000
	s_nop 0
	v_addc_co_u32_e32 v101, vcc, 0, v3, vcc
	v_lshl_add_u64 v[112:113], v[2:3], 0, s[10:11]
	s_movk_i32 s10, 0x3000
	v_lshl_add_u64 v[88:89], s[8:9], 0, v[158:159]
	v_add_co_u32_e32 v108, vcc, s10, v2
	s_mov_b64 s[10:11], 0x4800
	ds_read_b128 v[84:87], v222 offset:1152
	s_nop 0
	ds_read_b128 v[88:91], v222 offset:1024
	s_nop 0
	ds_read_b128 v[96:99], v222
	ds_read_b128 v[92:95], v222 offset:128
	v_addc_co_u32_e32 v109, vcc, 0, v3, vcc
	v_lshl_add_u64 v[116:117], v[2:3], 0, s[10:11]
	s_movk_i32 s10, 0x4000
	ds_read_b128 v[100:103], v222 offset:256
	s_nop 0
	ds_read_b128 v[104:107], v222 offset:384
	v_add_co_u32_e32 v2, vcc, s10, v2
	ds_read_b128 v[108:111], v222 offset:512
	s_nop 0
	ds_read_b128 v[112:115], v222 offset:640
	v_addc_co_u32_e32 v3, vcc, 0, v3, vcc
	ds_read_b128 v[120:123], v222 offset:768
	s_nop 0
	ds_read_b128 v[116:119], v222 offset:896
	v_add_u32_e32 v222, 0x500, v222
	v_lshl_add_u64 v[124:125], s[2:3], 0, v[156:157]
	s_mov_b32 s10, 0x19200000
	v_add_co_u32_e32 v2, vcc, s10, v124
	s_mov_b32 s10, 0x19201000
	s_nop 0
	v_addc_co_u32_e32 v3, vcc, 0, v125, vcc
	v_add_co_u32_e32 v130, vcc, s10, v124
	s_mov_b32 s10, 0x19202000
	s_nop 0
	v_addc_co_u32_e32 v131, vcc, 0, v125, vcc
	v_add_co_u32_e32 v128, vcc, s10, v124
	s_waitcnt vmcnt(4)
	v_lshlrev_b32_e32 v126, 16, v56
	v_addc_co_u32_e32 v129, vcc, 0, v125, vcc
	s_mov_b32 s10, 0x19203000
	v_lshlrev_b32_e32 v134, 16, v58
	v_lshlrev_b32_e32 v140, 16, v52
	v_add_co_u32_e32 v136, vcc, s10, v124
	v_and_b32_e32 v127, 0xffff0000, v56
	v_lshlrev_b32_e32 v144, 16, v54
	v_lshlrev_b32_e32 v155, 16, v60
	v_addc_co_u32_e32 v137, vcc, 0, v125, vcc
	v_and_b32_e32 v135, 0xffff0000, v58
	v_and_b32_e32 v139, 0xffff0000, v59
	v_and_b32_e32 v141, 0xffff0000, v52
	v_lshlrev_b32_e32 v173, 16, v62
	v_lshlrev_b32_e32 v177, 16, v64
	v_and_b32_e32 v145, 0xffff0000, v54
	v_and_b32_e32 v170, 0xffff0000, v60
	v_and_b32_e32 v174, 0xffff0000, v62
	v_and_b32_e32 v186, 0xffff0000, v64
	v_and_b32_e32 v133, 0xffff0000, v57
	v_and_b32_e32 v143, 0xffff0000, v53
	v_lshlrev_b32_e32 v138, 16, v59
	v_and_b32_e32 v172, 0xffff0000, v61
	s_bitcmp1_b32 s12, 0
	v_lshlrev_b32_e32 v132, 16, v57
	v_lshlrev_b32_e32 v142, 16, v53
	s_cselect_b32 s10, 0x4400, 0
	v_lshlrev_b32_e32 v171, 16, v61
	s_add_i32 s13, s10, 0
	v_lshlrev_b32_e32 v1, 1, v152
	v_lshlrev_b32_e32 v187, 16, v65
	s_add_i32 s13, s13, 0x11000
	v_add3_u32 v1, s13, v1, v196
	v_and_b32_e32 v147, 0xffff0000, v55
	v_and_b32_e32 v176, 0xffff0000, v63
	v_lshlrev_b32_e32 v146, 16, v55
	v_lshlrev_b32_e32 v175, 16, v63
	v_add_u32_e32 v206, s33, v150
	s_mov_b32 s10, 0x5040100
	s_cmpk_eq_i32 s33, 0xe00
	s_waitcnt lgkmcnt(0)
	v_fma_f32 v124, v96, v126, v88
	s_nop 0
	v_fma_f32 v125, v92, v134, v84
	v_fma_f32 v126, v97, v127, v89
	v_fma_f32 v127, v93, v135, v85
	v_fma_f32 v135, v95, v139, v87
	s_nop 0
	v_fmac_f32_e32 v124, v100, v140
	s_nop 0
	v_fmac_f32_e32 v125, v104, v144
	v_fmac_f32_e32 v126, v101, v141
	s_nop 0
	v_fmac_f32_e32 v124, v108, v155
	s_nop 0
	v_fmac_f32_e32 v125, v112, v173
	v_lshlrev_b32_e32 v139, 16, v66
	s_nop 0
	v_fmac_f32_e32 v124, v120, v177
	v_fmac_f32_e32 v127, v105, v145
	v_fmac_f32_e32 v126, v109, v170
	s_nop 0
	v_fmac_f32_e32 v125, v116, v139
	v_mul_f32_e32 v139, 0xbfb8aa3b, v124
	v_fmac_f32_e32 v127, v113, v174
	v_and_b32_e32 v140, 0xffff0000, v66
	v_fmac_f32_e32 v126, v121, v186
	v_exp_f32_e32 v139, v139
	v_fmac_f32_e32 v127, v117, v140
	v_mul_f32_e32 v140, 0xbfb8aa3b, v126
	v_exp_f32_e32 v140, v140
	v_fma_f32 v133, v99, v133, v91
	v_fmac_f32_e32 v133, v103, v143
	v_add_f32_e32 v139, 1.0, v139
	v_fma_f32 v134, v94, v138, v86
	v_fmac_f32_e32 v133, v111, v172
	v_and_b32_e32 v138, 0xffff0000, v65
	v_rcp_f32_e32 v139, v139
	v_fmac_f32_e32 v133, v123, v138
	v_add_f32_e32 v138, 1.0, v140
	v_fma_f32 v132, v98, v132, v90
	v_rcp_f32_e32 v138, v138
	v_fmac_f32_e32 v132, v102, v142
	v_fmac_f32_e32 v132, v110, v171
	v_mul_f32_e32 v124, v124, v139
	v_fmac_f32_e32 v132, v122, v187
	v_cvt_pk_bf16_f32 v124, v124, s0
	ds_write_b16 v1, v124
	v_mul_f32_e32 v124, v126, v138
	v_mul_f32_e32 v126, 0xbfb8aa3b, v132
	v_exp_f32_e32 v126, v126
	v_mul_f32_e32 v138, 0xbfb8aa3b, v133
	v_exp_f32_e32 v138, v138
	v_cvt_pk_bf16_f32 v124, v124, s0
	v_add_f32_e32 v126, 1.0, v126
	v_rcp_f32_e32 v126, v126
	ds_write_b16 v1, v124 offset:272
	v_add_f32_e32 v124, 1.0, v138
	v_rcp_f32_e32 v124, v124
	v_mul_f32_e32 v126, v132, v126
	v_cvt_pk_bf16_f32 v126, v126, s0
	ds_write_b16 v1, v126 offset:544
	v_mul_f32_e32 v126, 0xbfb8aa3b, v125
	v_exp_f32_e32 v126, v126
	v_mul_f32_e32 v132, 0xbfb8aa3b, v127
	v_exp_f32_e32 v132, v132
	v_mul_f32_e32 v124, v133, v124
	v_add_f32_e32 v126, 1.0, v126
	v_rcp_f32_e32 v126, v126
	v_fmac_f32_e32 v135, v107, v147
	v_cvt_pk_bf16_f32 v124, v124, s0
	v_fmac_f32_e32 v135, v115, v176
	v_and_b32_e32 v142, 0xffff0000, v67
	ds_write_b16 v1, v124 offset:816
	v_add_f32_e32 v124, 1.0, v132
	v_fmac_f32_e32 v134, v106, v146
	v_fmac_f32_e32 v135, v119, v142
	v_rcp_f32_e32 v124, v124
	v_fmac_f32_e32 v134, v114, v175
	v_lshlrev_b32_e32 v141, 16, v67
	v_mul_f32_e32 v125, v125, v126
	v_mul_f32_e32 v126, 0xbfb8aa3b, v135
	v_fmac_f32_e32 v134, v118, v141
	v_cvt_pk_bf16_f32 v125, v125, s0
	v_exp_f32_e32 v126, v126
	ds_write_b16 v1, v125 offset:1088
	v_mul_f32_e32 v125, 0xbfb8aa3b, v134
	v_mul_f32_e32 v124, v127, v124
	v_exp_f32_e32 v125, v125
	v_cvt_pk_bf16_f32 v124, v124, s0
	ds_write_b16 v1, v124 offset:1360
	v_add_f32_e32 v124, 1.0, v126
	v_rcp_f32_e32 v124, v124
	v_add_f32_e32 v125, 1.0, v125
	v_rcp_f32_e32 v125, v125
	v_lshlrev_b32_e32 v132, 16, v70
	v_mul_f32_e32 v124, v135, v124
	v_cvt_pk_bf16_f32 v124, v124, s0
	v_mul_f32_e32 v125, v134, v125
	ds_write_b16 v1, v124 offset:1904
	v_lshlrev_b32_e32 v124, 16, v68
	v_cvt_pk_bf16_f32 v125, v125, s0
	v_fma_f32 v88, v96, v124, v88
	v_fma_f32 v84, v92, v132, v84
	v_lshlrev_b32_e32 v92, 16, v72
	ds_write_b16 v1, v125 offset:1632
	v_and_b32_e32 v125, 0xffff0000, v68
	v_and_b32_e32 v133, 0xffff0000, v70
	v_fmac_f32_e32 v88, v100, v92
	v_lshlrev_b32_e32 v92, 16, v76
	v_fma_f32 v89, v97, v125, v89
	v_fma_f32 v85, v93, v133, v85
	v_and_b32_e32 v93, 0xffff0000, v72
	v_fmac_f32_e32 v88, v108, v92
	v_lshlrev_b32_e32 v92, 16, v80
	v_fmac_f32_e32 v89, v101, v93
	v_and_b32_e32 v93, 0xffff0000, v76
	v_fmac_f32_e32 v88, v120, v92
	v_fmac_f32_e32 v89, v109, v93
	v_and_b32_e32 v93, 0xffff0000, v80
	v_mul_f32_e32 v92, 0xbfb8aa3b, v88
	v_fmac_f32_e32 v89, v121, v93
	v_exp_f32_e32 v92, v92
	v_mul_f32_e32 v93, 0xbfb8aa3b, v89
	v_exp_f32_e32 v93, v93
	v_lshlrev_b32_e32 v126, 16, v69
	v_add_f32_e32 v92, 1.0, v92
	v_rcp_f32_e32 v92, v92
	v_lshlrev_b32_e32 v134, 16, v71
	v_add_f32_e32 v93, 1.0, v93
	v_fma_f32 v90, v98, v126, v90
	v_fma_f32 v86, v94, v134, v86
	v_lshlrev_b32_e32 v94, 16, v73
	v_rcp_f32_e32 v93, v93
	v_fmac_f32_e32 v90, v102, v94
	v_lshlrev_b32_e32 v94, 16, v77
	v_fmac_f32_e32 v90, v110, v94
	v_lshlrev_b32_e32 v94, 16, v81
	v_mul_f32_e32 v88, v88, v92
	v_fmac_f32_e32 v90, v122, v94
	v_cvt_pk_bf16_f32 v88, v88, s0
	ds_write_b16 v1, v88 offset:128
	v_mul_f32_e32 v88, v89, v93
	v_mul_f32_e32 v89, 0xbfb8aa3b, v90
	v_exp_f32_e32 v89, v89
	v_and_b32_e32 v127, 0xffff0000, v69
	v_and_b32_e32 v135, 0xffff0000, v71
	v_fmac_f32_e32 v91, v99, v127
	v_fmac_f32_e32 v87, v95, v135
	v_and_b32_e32 v95, 0xffff0000, v73
	v_fmac_f32_e32 v91, v103, v95
	v_and_b32_e32 v95, 0xffff0000, v77
	v_fmac_f32_e32 v91, v111, v95
	v_and_b32_e32 v95, 0xffff0000, v81
	v_add_f32_e32 v89, 1.0, v89
	v_fmac_f32_e32 v91, v123, v95
	v_rcp_f32_e32 v89, v89
	v_mul_f32_e32 v92, 0xbfb8aa3b, v91
	v_lshlrev_b32_e32 v96, 16, v74
	v_exp_f32_e32 v92, v92
	v_fmac_f32_e32 v84, v104, v96
	v_lshlrev_b32_e32 v96, 16, v78
	v_and_b32_e32 v97, 0xffff0000, v74
	v_fmac_f32_e32 v84, v112, v96
	v_lshlrev_b32_e32 v96, 16, v82
	v_mul_f32_e32 v89, v90, v89
	v_fmac_f32_e32 v85, v105, v97
	v_and_b32_e32 v97, 0xffff0000, v78
	v_fmac_f32_e32 v84, v116, v96
	v_cvt_pk_bf16_f32 v88, v88, s0
	v_cvt_pk_bf16_f32 v89, v89, s0
	v_fmac_f32_e32 v85, v113, v97
	v_and_b32_e32 v97, 0xffff0000, v82
	ds_write_b16 v1, v88 offset:400
	v_add_f32_e32 v88, 1.0, v92
	ds_write_b16 v1, v89 offset:672
	v_mul_f32_e32 v89, 0xbfb8aa3b, v84
	v_fmac_f32_e32 v85, v117, v97
	v_rcp_f32_e32 v88, v88
	v_exp_f32_e32 v89, v89
	v_mul_f32_e32 v90, 0xbfb8aa3b, v85
	v_exp_f32_e32 v90, v90
	v_mul_f32_e32 v88, v91, v88
	v_add_f32_e32 v89, 1.0, v89
	v_cvt_pk_bf16_f32 v88, v88, s0
	v_rcp_f32_e32 v89, v89
	ds_write_b16 v1, v88 offset:944
	v_add_f32_e32 v88, 1.0, v90
	v_lshlrev_b32_e32 v98, 16, v75
	v_and_b32_e32 v99, 0xffff0000, v75
	v_rcp_f32_e32 v88, v88
	v_fmac_f32_e32 v86, v106, v98
	v_fmac_f32_e32 v87, v107, v99
	v_lshlrev_b32_e32 v98, 16, v79
	v_and_b32_e32 v99, 0xffff0000, v79
	v_fmac_f32_e32 v86, v114, v98
	v_fmac_f32_e32 v87, v115, v99
	v_lshlrev_b32_e32 v98, 16, v83
	v_and_b32_e32 v99, 0xffff0000, v83
	v_mul_f32_e32 v84, v84, v89
	v_fmac_f32_e32 v86, v118, v98
	v_fmac_f32_e32 v87, v119, v99
	v_cvt_pk_bf16_f32 v84, v84, s0
	ds_write_b16 v1, v84 offset:1216
	v_mul_f32_e32 v84, v85, v88
	v_mul_f32_e32 v85, 0xbfb8aa3b, v86
	v_mul_f32_e32 v88, 0xbfb8aa3b, v87
	v_exp_f32_e32 v85, v85
	v_exp_f32_e32 v88, v88
	v_cvt_pk_bf16_f32 v84, v84, s0
	ds_write_b16 v1, v84 offset:1488
	v_add_f32_e32 v85, 1.0, v85
	v_add_f32_e32 v84, 1.0, v88
	v_rcp_f32_e32 v85, v85
	v_rcp_f32_e32 v84, v84
	v_lshl_add_u64 v[176:177], s[2:3], 0, v[166:167]
	v_mul_f32_e32 v85, v86, v85
	v_mul_f32_e32 v84, v87, v84
	v_cvt_pk_bf16_f32 v85, v85, s0
	v_cvt_pk_bf16_f32 v84, v84, s0
	ds_write_b16 v1, v85 offset:1760
	ds_write_b16 v1, v84 offset:2032
	v_add_u32_e32 v1, s33, v200
	v_add_u32_e32 v84, 0x23000, v206
	ds_read_b32 v155, v1
	ds_read_b128 v[84:87], v84
	v_add_u32_e32 v1, 0x22000, v206
	ds_read_b128 v[88:91], v1
	global_load_dwordx4 v[92:95], v[130:131], off offset:-4096
	global_load_dwordx4 v[100:103], v[130:131], off
	s_waitcnt lgkmcnt(1)
	v_sub_f32_e32 v1, v155, v84
	v_mul_f32_e32 v1, 0x3fb8aa3b, v1
	v_exp_f32_e32 v1, v1
	v_sub_f32_e32 v84, v155, v85
	v_mul_f32_e32 v84, 0x3fb8aa3b, v84
	v_sub_f32_e32 v85, v155, v87
	v_mul_f32_e32 v1, v20, v1
	s_waitcnt lgkmcnt(0)
	v_mul_f32_e32 v1, v88, v1
	v_exp_f32_e32 v88, v84
	v_sub_f32_e32 v84, v155, v86
	v_mul_f32_e32 v84, 0x3fb8aa3b, v84
	v_mul_f32_e32 v85, 0x3fb8aa3b, v85
	v_exp_f32_e32 v84, v84
	v_exp_f32_e32 v85, v85
	v_mul_f32_e32 v86, v21, v88
	v_mul_f32_e32 v86, v89, v86
	v_cndmask_b32_e64 v1, v1, 0, s[20:21]
	v_pk_mul_f32 v[84:85], v[22:23], v[84:85]
	v_cndmask_b32_e64 v86, 0, v86, s[22:23]
	v_pk_mul_f32 v[84:85], v[90:91], v[84:85]
	v_cvt_pk_bf16_f32 v86, v1, v86
	v_cvt_pk_bf16_f32 v1, v84, v85
	v_cndmask_b32_e64 v84, v1, 0, s[26:27]
	v_lshrrev_b32_e32 v1, 16, v1
	v_cndmask_b32_e64 v1, v1, 0, s[24:25]
	v_perm_b32 v87, v1, v84, s10
	ds_write_b64 v195, v[86:87]
	v_add_u32_e32 v1, 0x23040, v206
	ds_read_b128 v[84:87], v1
	v_add_u32_e32 v1, 0x22040, v206
	ds_read_b128 v[88:91], v1
	s_waitcnt lgkmcnt(1)
	v_sub_f32_e32 v1, v155, v84
	v_mul_f32_e32 v1, 0x3fb8aa3b, v1
	v_exp_f32_e32 v84, v1
	v_sub_f32_e32 v1, v155, v85
	v_mul_f32_e32 v1, 0x3fb8aa3b, v1
	v_exp_f32_e32 v85, v1
	v_sub_f32_e32 v1, v155, v86
	v_mul_f32_e32 v1, 0x3fb8aa3b, v1
	v_exp_f32_e32 v86, v1
	v_sub_f32_e32 v1, v155, v87
	v_mul_f32_e32 v1, 0x3fb8aa3b, v1
	v_exp_f32_e32 v87, v1
	v_pk_mul_f32 v[84:85], v[24:25], v[84:85]
	v_pk_mul_f32 v[86:87], v[26:27], v[86:87]
	s_waitcnt lgkmcnt(0)
	v_pk_mul_f32 v[84:85], v[88:89], v[84:85]
	v_pk_mul_f32 v[86:87], v[90:91], v[86:87]
	v_cvt_pk_bf16_f32 v1, v84, v85
	v_cndmask_b32_e64 v84, v1, 0, s[30:31]
	v_lshrrev_b32_e32 v1, 16, v1
	v_cndmask_b32_e64 v1, v1, 0, s[28:29]
	v_perm_b32 v84, v1, v84, s10
	v_cvt_pk_bf16_f32 v1, v86, v87
	v_cndmask_b32_e64 v85, v1, 0, s[36:37]
	v_lshrrev_b32_e32 v1, 16, v1
	v_cndmask_b32_e64 v1, v1, 0, s[34:35]
	v_perm_b32 v85, v1, v85, s10
	ds_write_b64 v195, v[84:85] offset:32
	v_add_u32_e32 v1, 0x23080, v206
	ds_read_b128 v[88:91], v1
	v_add_u32_e32 v1, 0x22080, v206
	global_load_dwordx4 v[112:115], v[136:137], off
	global_load_dwordx4 v[84:87], v[136:137], off offset:64
	ds_read_b128 v[96:99], v1
	s_waitcnt lgkmcnt(1)
	v_sub_f32_e32 v1, v155, v88
	v_mul_f32_e32 v1, 0x3fb8aa3b, v1
	v_exp_f32_e32 v104, v1
	v_sub_f32_e32 v1, v155, v89
	v_mul_f32_e32 v1, 0x3fb8aa3b, v1
	v_exp_f32_e32 v105, v1
	v_sub_f32_e32 v1, v155, v90
	v_mul_f32_e32 v1, 0x3fb8aa3b, v1
	v_exp_f32_e32 v106, v1
	v_sub_f32_e32 v1, v155, v91
	v_mul_f32_e32 v1, 0x3fb8aa3b, v1
	v_exp_f32_e32 v107, v1
	v_pk_mul_f32 v[104:105], v[28:29], v[104:105]
	global_load_dwordx4 v[108:111], v[2:3], off offset:64
	global_load_dwordx4 v[88:91], v[2:3], off offset:128
	s_waitcnt lgkmcnt(0)
	v_pk_mul_f32 v[96:97], v[96:97], v[104:105]
	v_pk_mul_f32 v[104:105], v[30:31], v[106:107]
	v_cvt_pk_bf16_f32 v1, v96, v97
	v_cndmask_b32_e64 v96, v1, 0, s[40:41]
	v_lshrrev_b32_e32 v1, 16, v1
	v_pk_mul_f32 v[98:99], v[98:99], v[104:105]
	v_cndmask_b32_e64 v1, v1, 0, s[38:39]
	v_perm_b32 v96, v1, v96, s10
	v_cvt_pk_bf16_f32 v1, v98, v99
	v_cndmask_b32_e64 v97, v1, 0, s[44:45]
	v_lshrrev_b32_e32 v1, 16, v1
	v_cndmask_b32_e64 v1, v1, 0, s[42:43]
	v_perm_b32 v97, v1, v97, s10
	ds_write_b64 v195, v[96:97] offset:64
	v_add_u32_e32 v1, 0x230c0, v206
	ds_read_b128 v[104:107], v1
	v_add_u32_e32 v1, 0x220c0, v206
	global_load_dwordx4 v[116:119], v[130:131], off offset:64
	global_load_dwordx4 v[96:99], v[130:131], off offset:128
	ds_read_b128 v[120:123], v1
	s_waitcnt lgkmcnt(1)
	v_sub_f32_e32 v1, v155, v104
	v_mul_f32_e32 v1, 0x3fb8aa3b, v1
	v_exp_f32_e32 v132, v1
	v_sub_f32_e32 v1, v155, v105
	v_mul_f32_e32 v1, 0x3fb8aa3b, v1
	v_exp_f32_e32 v133, v1
	v_sub_f32_e32 v1, v155, v106
	v_mul_f32_e32 v1, 0x3fb8aa3b, v1
	v_exp_f32_e32 v134, v1
	v_sub_f32_e32 v1, v155, v107
	v_mul_f32_e32 v1, 0x3fb8aa3b, v1
	v_exp_f32_e32 v135, v1
	global_load_dwordx4 v[124:127], v[128:129], off offset:64
	global_load_dwordx4 v[104:107], v[2:3], off offset:192
	v_pk_mul_f32 v[2:3], v[32:33], v[132:133]
	s_waitcnt lgkmcnt(0)
	v_pk_mul_f32 v[2:3], v[120:121], v[2:3]
	v_pk_mul_f32 v[120:121], v[34:35], v[134:135]
	v_cvt_pk_bf16_f32 v1, v2, v3
	v_cndmask_b32_e64 v2, v1, 0, s[48:49]
	v_lshrrev_b32_e32 v1, 16, v1
	v_pk_mul_f32 v[120:121], v[122:123], v[120:121]
	v_cndmask_b32_e64 v1, v1, 0, s[46:47]
	v_perm_b32 v2, v1, v2, s10
	v_cvt_pk_bf16_f32 v1, v120, v121
	v_cndmask_b32_e64 v3, v1, 0, s[52:53]
	v_lshrrev_b32_e32 v1, 16, v1
	v_cndmask_b32_e64 v1, v1, 0, s[50:51]
	v_perm_b32 v3, v1, v3, s10
	ds_write_b64 v195, v[2:3] offset:96
	v_add_u32_e32 v1, 0x23100, v206
	ds_read_b128 v[132:135], v1
	v_add_u32_e32 v1, 0x22100, v206
	global_load_dwordx4 v[144:147], v[136:137], off offset:-4096
	global_load_dwordx4 v[120:123], v[130:131], off offset:192
	ds_read_b128 v[138:141], v1
	s_waitcnt lgkmcnt(1)
	v_sub_f32_e32 v1, v155, v132
	v_mul_f32_e32 v1, 0x3fb8aa3b, v1
	v_exp_f32_e32 v2, v1
	v_sub_f32_e32 v1, v155, v133
	v_mul_f32_e32 v1, 0x3fb8aa3b, v1
	v_exp_f32_e32 v3, v1
	v_sub_f32_e32 v1, v155, v134
	v_mul_f32_e32 v1, 0x3fb8aa3b, v1
	v_exp_f32_e32 v142, v1
	v_sub_f32_e32 v1, v155, v135
	v_mul_f32_e32 v1, 0x3fb8aa3b, v1
	v_exp_f32_e32 v143, v1
	v_pk_mul_f32 v[2:3], v[36:37], v[2:3]
	global_load_dwordx4 v[132:135], v[128:129], off offset:128
	s_nop 0
	global_load_dwordx4 v[128:131], v[128:129], off offset:192
	s_waitcnt lgkmcnt(0)
	v_pk_mul_f32 v[2:3], v[138:139], v[2:3]
	v_pk_mul_f32 v[138:139], v[38:39], v[142:143]
	v_cvt_pk_bf16_f32 v1, v2, v3
	v_cndmask_b32_e64 v2, v1, 0, s[56:57]
	v_lshrrev_b32_e32 v1, 16, v1
	v_pk_mul_f32 v[138:139], v[140:141], v[138:139]
	v_cndmask_b32_e64 v1, v1, 0, s[54:55]
	v_perm_b32 v2, v1, v2, s10
	v_cvt_pk_bf16_f32 v1, v138, v139
	v_cndmask_b32_e64 v3, v1, 0, s[60:61]
	v_lshrrev_b32_e32 v1, 16, v1
	v_cndmask_b32_e64 v1, v1, 0, s[58:59]
	v_perm_b32 v3, v1, v3, s10
	ds_write_b64 v195, v[2:3] offset:128
	v_add_u32_e32 v1, 0x23140, v206
	ds_read_b128 v[170:173], v1
	v_add_u32_e32 v1, 0x22140, v206
	global_load_dwordx4 v[140:143], v[136:137], off offset:128
	s_nop 0
	global_load_dwordx4 v[136:139], v[136:137], off offset:192
	ds_read_b128 v[186:189], v1
	s_waitcnt lgkmcnt(1)
	v_sub_f32_e32 v1, v155, v170
	v_mul_f32_e32 v1, 0x3fb8aa3b, v1
	v_exp_f32_e32 v2, v1
	v_sub_f32_e32 v1, v155, v171
	v_mul_f32_e32 v1, 0x3fb8aa3b, v1
	v_exp_f32_e32 v3, v1
	v_sub_f32_e32 v1, v155, v172
	v_mul_f32_e32 v1, 0x3fb8aa3b, v1
	v_exp_f32_e32 v192, v1
	v_sub_f32_e32 v1, v155, v173
	global_load_dwordx2 v[190:191], v[176:177], off offset:-64
	global_load_dwordx2 v[174:175], v[176:177], off offset:-32
	global_load_dwordx2 v[172:173], v[176:177], off
	global_load_dwordx2 v[170:171], v[176:177], off offset:32
	v_mul_f32_e32 v1, 0x3fb8aa3b, v1
	v_exp_f32_e32 v193, v1
	v_pk_mul_f32 v[2:3], v[40:41], v[2:3]
	s_waitcnt lgkmcnt(0)
	v_pk_mul_f32 v[2:3], v[186:187], v[2:3]
	v_pk_mul_f32 v[186:187], v[42:43], v[192:193]
	v_cvt_pk_bf16_f32 v1, v2, v3
	v_cndmask_b32_e64 v2, v1, 0, s[64:65]
	v_lshrrev_b32_e32 v1, 16, v1
	v_pk_mul_f32 v[186:187], v[188:189], v[186:187]
	v_cndmask_b32_e64 v1, v1, 0, s[62:63]
	v_perm_b32 v2, v1, v2, s10
	v_cvt_pk_bf16_f32 v1, v186, v187
	v_cndmask_b32_e64 v3, v1, 0, s[68:69]
	v_lshrrev_b32_e32 v1, 16, v1
	v_cndmask_b32_e64 v1, v1, 0, s[66:67]
	v_perm_b32 v3, v1, v3, s10
	ds_write_b64 v195, v[2:3] offset:160
	v_add_u32_e32 v1, 0x23180, v206
	ds_read_b128 v[186:189], v1
	v_add_u32_e32 v1, 0x22180, v206
	ds_read_b128 v[202:205], v1
	s_waitcnt lgkmcnt(1)
	v_sub_f32_e32 v1, v155, v186
	v_mul_f32_e32 v1, 0x3fb8aa3b, v1
	v_exp_f32_e32 v2, v1
	v_sub_f32_e32 v1, v155, v187
	v_mul_f32_e32 v1, 0x3fb8aa3b, v1
	v_exp_f32_e32 v3, v1
	v_sub_f32_e32 v1, v155, v188
	v_mul_f32_e32 v1, 0x3fb8aa3b, v1
	v_exp_f32_e32 v186, v1
	v_sub_f32_e32 v1, v155, v189
	v_mul_f32_e32 v1, 0x3fb8aa3b, v1
	v_exp_f32_e32 v187, v1
	v_pk_mul_f32 v[2:3], v[44:45], v[2:3]
	v_pk_mul_f32 v[186:187], v[46:47], v[186:187]
	s_waitcnt lgkmcnt(0)
	v_pk_mul_f32 v[2:3], v[202:203], v[2:3]
	v_pk_mul_f32 v[186:187], v[204:205], v[186:187]
	v_cvt_pk_bf16_f32 v1, v2, v3
	v_cndmask_b32_e64 v2, v1, 0, s[72:73]
	v_lshrrev_b32_e32 v1, 16, v1
	v_cndmask_b32_e64 v1, v1, 0, s[70:71]
	v_perm_b32 v2, v1, v2, s10
	v_cvt_pk_bf16_f32 v1, v186, v187
	v_cndmask_b32_e64 v3, v1, 0, s[76:77]
	v_lshrrev_b32_e32 v1, 16, v1
	v_cndmask_b32_e64 v1, v1, 0, s[74:75]
	v_perm_b32 v3, v1, v3, s10
	ds_write_b64 v195, v[2:3] offset:192
	v_add_u32_e32 v1, 0x231c0, v206
	ds_read_b128 v[186:189], v1
	v_add_u32_e32 v1, 0x221c0, v206
	ds_read_b128 v[202:205], v1
	s_waitcnt lgkmcnt(1)
	v_sub_f32_e32 v1, v155, v186
	v_mul_f32_e32 v1, 0x3fb8aa3b, v1
	v_exp_f32_e32 v2, v1
	v_sub_f32_e32 v1, v155, v187
	v_mul_f32_e32 v1, 0x3fb8aa3b, v1
	v_exp_f32_e32 v3, v1
	v_sub_f32_e32 v1, v155, v188
	v_mul_f32_e32 v1, 0x3fb8aa3b, v1
	v_exp_f32_e32 v186, v1
	v_sub_f32_e32 v1, v155, v189
	v_mul_f32_e32 v1, 0x3fb8aa3b, v1
	v_exp_f32_e32 v187, v1
	v_pk_mul_f32 v[2:3], v[48:49], v[2:3]
	v_pk_mul_f32 v[186:187], v[50:51], v[186:187]
	s_waitcnt lgkmcnt(0)
	v_pk_mul_f32 v[2:3], v[202:203], v[2:3]
	v_pk_mul_f32 v[186:187], v[204:205], v[186:187]
	v_cvt_pk_bf16_f32 v1, v2, v3
	v_cndmask_b32_e64 v2, v1, 0, s[80:81]
	v_lshrrev_b32_e32 v1, 16, v1
	v_cndmask_b32_e64 v1, v1, 0, s[78:79]
	v_perm_b32 v2, v1, v2, s10
	v_cvt_pk_bf16_f32 v1, v186, v187
	v_cndmask_b32_e64 v3, v1, 0, s[84:85]
	v_lshrrev_b32_e32 v1, 16, v1
	v_cndmask_b32_e64 v1, v1, 0, s[82:83]
	v_perm_b32 v3, v1, v3, s10
	ds_write_b64 v195, v[2:3] offset:224
	s_waitcnt lgkmcnt(0)
	s_barrier
	s_cbranch_scc1 .LBB0_1125
	v_readlane_b32 s10, v255, 42
	v_readlane_b32 s11, v255, 43
	s_cmp_eq_u64 s[10:11], -1
	s_cbranch_scc0 .Lp3x_slow
	v_lshl_add_u64 v[192:193], s[2:3], 0, v[168:169]
	s_mov_b32 s10, 0x31fac80
	s_mov_b32 s11, 0
	v_lshl_add_u64 v[2:3], v[192:193], 0, s[10:11]
	global_load_dwordx4 v[56:59], v[2:3], off
	s_mov_b32 s10, 0x31fd080
	s_mov_b32 s11, 0
	v_lshl_add_u64 v[2:3], v[192:193], 0, s[10:11]
	global_load_dwordx4 v[52:55], v[2:3], off
	s_mov_b32 s10, 0x31ff480
	s_mov_b32 s11, 0
	v_lshl_add_u64 v[2:3], v[192:193], 0, s[10:11]
	global_load_dwordx4 v[60:63], v[2:3], off
	s_mov_b32 s10, 0x3201880
	s_mov_b32 s11, 0
	v_lshl_add_u64 v[2:3], v[192:193], 0, s[10:11]
	global_load_dwordx4 v[64:67], v[2:3], off
	s_mov_b32 s10, 0x328ac80
	s_mov_b32 s11, 0
	v_lshl_add_u64 v[2:3], v[192:193], 0, s[10:11]
	global_load_dwordx4 v[68:71], v[2:3], off
	s_mov_b32 s10, 0x328d080
	s_mov_b32 s11, 0
	v_lshl_add_u64 v[2:3], v[192:193], 0, s[10:11]
	global_load_dwordx4 v[72:75], v[2:3], off
	s_mov_b32 s10, 0x328f480
	s_mov_b32 s11, 0
	v_lshl_add_u64 v[2:3], v[192:193], 0, s[10:11]
	global_load_dwordx4 v[76:79], v[2:3], off
	s_mov_b32 s10, 0x3291880
	s_mov_b32 s11, 0
	v_lshl_add_u64 v[2:3], v[192:193], 0, s[10:11]
	global_load_dwordx4 v[80:83], v[2:3], off
	s_branch .LBB0_1125
.Lp3x_slow:
	v_mov_b32_e32 v54, v0
	v_mov_b32_e32 v55, v0
	v_mov_b32_e32 v52, v0
	v_mov_b32_e32 v53, v0
	v_mov_b64_e32 v[58:59], v[54:55]
	v_lshl_add_u64 v[192:193], s[2:3], 0, v[168:169]
	v_mov_b64_e32 v[56:57], v[52:53]
	s_mov_b64 s[10:11], exec
	v_readlane_b32 vcc_lo, v255, 42
	v_readlane_b32 vcc_hi, v255, 43
	s_and_b64 vcc, s[10:11], vcc
	s_mov_b64 exec, vcc
	s_cbranch_execz .LBB0_1129
	v_add_co_u32_e32 v2, vcc, 0x31fa000, v192
	s_nop 1
	v_addc_co_u32_e32 v3, vcc, 0, v193, vcc
	global_load_dwordx4 v[56:59], v[2:3], off offset:3200
